# stack5 + G1 next-iteration LR/K/V row touch-prefetch
# speedup vs baseline: 1.0063x; 1.0000x over previous
; #define LAS __attribute__((address_space(3)))
; #define MEMBAR() asm volatile("" ::: "memory")
; __device__ __forceinline__ void gla_gates(const LAS float* lrs, const float* w2, const float* gbias, int h, int d, int w, float (&pf)[16], float (&sb)[16]) {
;     ...
;     for (int r = 0; r < 16; ++r) { wf[r] = w2[r * 256 + h * 64 + d]; wb[r] = w2[(16 + r) * 256 + h * 64 + d]; }
;     const float bf = gbias[h * 64 + d], bb = gbias[256 + h * 64 + d];
; __device__ __forceinline__ void gla_g1(LAS unsigned char* lds, const bf16_t* KAT, const bf16_t* VAT, const float* LR, const float* w2, const float* gbias, bf16_t* DS, float* DEC, float* BC) {
;     ...
;         const int uid = it * 2 + half, c = uid & 31, h = (uid >> 5) & 3, bl = uid >> 7;
;         const size_t row0 = (size_t)bl * SEQ + c * 64;
;         const bf16_t* kat = KAT + ((size_t)(bl * 4 + h) * 64) * SEQ + c * 64;
;         const bf16_t* vat = VAT + ((size_t)(bl * 4 + h) * 128) * SEQ + c * 64;
;         const f32x4 l0 = *(const f32x4*)(LR + row0 * 32 + t256 * 8), l1 = *(const f32x4*)(LR + row0 * 32 + t256 * 8 + 4);
;         bf16x8 bfr[2][2], kraw[2][4];
; #pragma unroll
;         for (int t = 0; t < 2; ++t) {
; #pragma unroll
;             for (int e = 0; e < 2; ++e) bfr[t][e] = *(const bf16x8*)(vat + (size_t)(16 * (2 * w + e) + fr) * SEQ + 32 * t + 8 * g);
; #pragma unroll
;             for (int mb = 0; mb < 4; ++mb) kraw[t][mb] = *(const bf16x8*)(kat + (size_t)(16 * mb + fr) * SEQ + 32 * t + 8 * g);
;         }
;         MEMBAR();
;         *(LAS f32x4*)(LRS + t256 * 8) = l0; *(LAS f32x4*)(LRS + t256 * 8 + 4) = l1;
;         __syncthreads();
.LBB0_497:
	v_bfe_u32 v59, v58, 5, 2
	v_ashrrev_i32_e32 v0, 7, v58
	v_lshl_or_b32 v2, v0, 2, v59
	v_ashrrev_i32_e32 v3, 31, v2
	v_readlane_b32 s4, v252, 39
	v_lshlrev_b64 v[4:5], 18, v[2:3]
	v_readlane_b32 s5, v252, 40
	v_lshlrev_b64 v[2:3], 19, v[2:3]
	v_ashrrev_i32_e32 v1, 31, v0
	v_lshl_add_u64 v[4:5], s[4:5], 0, v[4:5]
	v_readlane_b32 s4, v253, 7
	v_readlane_b32 s5, v253, 8
	v_and_b32_e32 v6, 0x7c0, v129
	v_lshlrev_b32_e32 v190, 1, v6
	v_lshl_add_u64 v[2:3], s[4:5], 0, v[2:3]
	v_readlane_b32 s4, v252, 43
	v_lshlrev_b64 v[0:1], 18, v[0:1]
	v_readlane_b32 s5, v252, 44
	v_lshl_add_u64 v[4:5], v[4:5], 0, v[190:191]
	v_lshl_add_u64 v[2:3], v[2:3], 0, v[190:191]
	v_lshl_add_u64 v[0:1], s[4:5], 0, v[0:1]
	v_lshlrev_b32_e32 v190, 7, v6
	v_lshl_add_u64 v[0:1], v[0:1], 0, v[190:191]
	v_mov_b32_e32 v61, v191
	v_lshl_add_u64 v[0:1], v[0:1], 0, v[60:61]
	global_load_dwordx4 v[76:79], v[0:1], off offset:16
	global_load_dwordx4 v[80:83], v[0:1], off
	v_mov_b32_e32 v63, v191
	v_lshl_add_u64 v[8:9], v[4:5], 0, v[62:63]
	v_mov_b32_e32 v69, v191
	v_mov_b32_e32 v71, v191
	v_lshl_add_u64 v[10:11], v[8:9], 0, v[68:69]
	v_lshl_add_u64 v[4:5], v[8:9], 0, v[70:71]
	v_mov_b32_e32 v73, v191
	v_lshl_add_u64 v[0:1], v[2:3], 0, v[62:63]
	v_mov_b32_e32 v65, v191
	v_mov_b32_e32 v67, v191
	global_load_dwordx4 v[44:47], v[10:11], off
	global_load_dwordx4 v[40:43], v[4:5], off
	v_lshl_add_u64 v[4:5], v[8:9], 0, v[72:73]
	v_mov_b32_e32 v75, v191
	v_lshl_add_u64 v[2:3], v[0:1], 0, v[64:65]
	v_lshl_add_u64 v[0:1], v[0:1], 0, v[66:67]
	global_load_dwordx4 v[36:39], v[4:5], off
	v_lshl_add_u64 v[4:5], v[8:9], 0, v[74:75]
	v_lshl_add_u64 v[8:9], v[8:9], 0, 64
	global_load_dwordx4 v[20:23], v[2:3], off
	global_load_dwordx4 v[24:27], v[0:1], off
	global_load_dwordx4 v[32:35], v[4:5], off
	s_nop 0
	global_load_dwordx4 v[4:7], v[2:3], off offset:64
	s_nop 0
	global_load_dwordx4 v[0:3], v[0:1], off offset:64
	v_lshl_or_b32 v190, v59, 8, v50
	global_load_dwordx4 v[28:31], v[10:11], off offset:64
	v_lshl_add_u64 v[10:11], v[8:9], 0, v[70:71]
	global_load_dwordx4 v[16:19], v[10:11], off
	v_lshl_add_u64 v[10:11], v[8:9], 0, v[72:73]
	v_lshl_add_u64 v[8:9], v[8:9], 0, v[74:75]
	global_load_dwordx4 v[12:15], v[10:11], off
	s_movk_i32 s5, 0x4000
	global_load_dwordx4 v[8:11], v[8:9], off
	v_readlane_b32 s98, v254, 18
	v_lshrrev_b32_e32 v211, 6, v250
	v_and_b32_e32 v212, 63, v250
	v_and_b32_e32 v211, 3, v211
	v_add_u32_e32 v210, s98, v58
	v_mov_b32_e32 v213, 0
	s_mov_b32 m0, 0x20000
	v_readfirstlane_b32 s99, v210
	v_readfirstlane_b32 s98, v211
	s_nop 1
	s_cmpk_gt_i32 s99, 0xbff
	s_cbranch_scc1 .Lg1_touch_done
	s_and_b32 s100, s99, 31
	s_cmp_eq_u32 s98, 0
	s_cbranch_scc0 .Lg1_touch_kv
	s_lshr_b32 s101, s99, 7
	s_lshl_b32 s101, s101, 11
	s_lshl_b32 s100, s100, 6
	s_add_i32 s100, s100, s101
	v_add_u32_e32 v212, s100, v212
	v_lshlrev_b32_e32 v212, 7, v212
	v_readlane_b32 s100, v252, 43
	v_readlane_b32 s101, v252, 44
	s_branch .Lg1_touch_go
.Lg1_touch_kv:
	s_lshl_b32 s100, s100, 7
	s_lshr_b32 s101, s99, 5
	s_cmp_eq_u32 s98, 1
	s_cbranch_scc0 .Lg1_touch_v
	s_lshl_b32 s101, s101, 6
	v_add_u32_e32 v212, s101, v212
	v_lshlrev_b32_e32 v212, 12, v212
	v_add_u32_e32 v212, s100, v212
	v_readlane_b32 s100, v252, 39
	v_readlane_b32 s101, v252, 40
	s_branch .Lg1_touch_go
.Lg1_touch_v:
	s_lshl_b32 s101, s101, 7
	s_add_i32 s98, s98, -2
	s_lshl_b32 s98, s98, 6
	s_add_i32 s101, s101, s98
	v_add_u32_e32 v212, s101, v212
	v_lshlrev_b32_e32 v212, 12, v212
	v_add_u32_e32 v212, s100, v212
	v_readlane_b32 s100, v253, 7
	v_readlane_b32 s101, v253, 8
.Lg1_touch_go:
	s_nop 1
	v_lshl_add_u64 v[214:215], s[100:101], 0, v[212:213]
	global_load_lds_dword v[214:215], off
.Lg1_touch_done:
	s_movk_i32 s4, 0x2000
	s_mov_b32 s10, 0xbf317218
	s_waitcnt vmcnt(12)
	ds_write_b128 v126, v[80:83] offset:36864
	ds_write_b128 v126, v[76:79] offset:36880
	v_lshl_add_u64 v[78:79], s[48:49], 0, v[190:191]
	v_add_co_u32_e32 v80, vcc, s5, v78
	s_movk_i32 s5, 0x5000
	s_nop 0
	v_addc_co_u32_e32 v81, vcc, 0, v79, vcc
	v_add_co_u32_e32 v82, vcc, s5, v78
	s_movk_i32 s5, 0x1000
	s_nop 0
	v_addc_co_u32_e32 v83, vcc, 0, v79, vcc
	s_waitcnt lgkmcnt(0)
	s_barrier
	global_load_dword v76, v190, s[48:49]
	global_load_dword v77, v[82:83], off offset:-4096
	global_load_dword v90, v190, s[48:49] offset:1024
	global_load_dword v91, v[80:81], off offset:1024
	global_load_dword v88, v190, s[48:49] offset:2048
	global_load_dword v89, v[80:81], off offset:2048
	global_load_dword v86, v190, s[48:49] offset:3072
	global_load_dword v87, v[80:81], off offset:3072
	v_add_co_u32_e32 v80, vcc, s5, v78
	s_movk_i32 s5, 0x6000
	s_nop 0
	v_addc_co_u32_e32 v81, vcc, 0, v79, vcc
	v_add_co_u32_e32 v84, vcc, s4, v78
	s_mov_b32 s4, 0x3d800000
	s_nop 0
	v_addc_co_u32_e32 v85, vcc, 0, v79, vcc
	global_load_dword v98, v[84:85], off offset:-4096
	global_load_dword v99, v[82:83], off
	global_load_dword v94, v[80:81], off offset:1024
	global_load_dword v95, v[82:83], off offset:1024
	global_load_dword v96, v[80:81], off offset:2048
	global_load_dword v97, v[82:83], off offset:2048
	global_load_dword v100, v[80:81], off offset:3072
	global_load_dword v101, v[82:83], off offset:3072
	global_load_dword v92, v[84:85], off
	v_add_co_u32_e32 v80, vcc, s5, v78
	s_movk_i32 s5, 0x7000
	s_nop 0
	v_addc_co_u32_e32 v81, vcc, 0, v79, vcc
	v_add_co_u32_e32 v108, vcc, s5, v78
	s_movk_i32 s5, 0x3000
	s_nop 0
	v_addc_co_u32_e32 v109, vcc, 0, v79, vcc
	v_add_co_u32_e32 v78, vcc, s5, v78
	global_load_dword v93, v[108:109], off offset:-4096
	global_load_dword v102, v[84:85], off offset:1024
	global_load_dword v103, v[80:81], off offset:1024
	global_load_dword v104, v[84:85], off offset:2048
	global_load_dword v105, v[80:81], off offset:2048
	global_load_dword v106, v[84:85], off offset:3072
	global_load_dword v107, v[80:81], off offset:3072
	v_addc_co_u32_e32 v79, vcc, 0, v79, vcc
	global_load_dword v84, v[78:79], off
	global_load_dword v85, v[108:109], off
	global_load_dword v82, v[78:79], off offset:1024
	global_load_dword v83, v[108:109], off offset:1024
	global_load_dword v80, v[78:79], off offset:2048
	global_load_dword v81, v[108:109], off offset:2048
	s_nop 0
	global_load_dword v78, v[78:79], off offset:3072
	s_nop 0
	global_load_dword v79, v[108:109], off offset:3072
	s_nop 0
	global_load_dword v108, v190, s[50:51]
	global_load_dword v109, v190, s[50:51] offset:1024
	ds_read_b128 v[110:113], v127 offset:36864
	ds_read_b128 v[114:117], v127 offset:36880
	ds_read_b128 v[118:121], v127 offset:36896
	ds_read_b128 v[122:125], v127 offset:36912
	ds_read_b128 v[130:133], v127 offset:36928
	s_waitcnt lgkmcnt(4)
; #define LAS __attribute__((address_space(3)))
; __device__ __forceinline__ float log_sigmoid_fast(float z) {
;     const float e = __builtin_amdgcn_exp2f(-1.44269504088896f * fabsf(z));
;     return fminf(z, 0.f) - 0.693147180559945f * __builtin_amdgcn_logf(1.0f + e);
; }
; __device__ __forceinline__ void gla_gates(const LAS float* lrs, const float* w2, const float* gbias, int h, int d, int w, float (&pf)[16], float (&sb)[16]) {
;     ...
; #pragma unroll
;     for (int j = 0; j < 16; ++j) {
;         const LAS float* lr = lrs + (w * 16 + j) * 32;
;         f32x2_t z2 = {bf, bb};
; #pragma unroll
;         for (int r4 = 0; r4 < 4; ++r4) { const f32x4 a = *(const LAS f32x4*)(lr + 4 * r4), b = *(const LAS f32x4*)(lr + 16 + 4 * r4);
; #pragma unroll
;             for (int q = 0; q < 4; ++q) { const f32x2_t x2 = {a[q], b[q]}, w2v = {wf[4 * r4 + q], wb[4 * r4 + q]}; z2 = __builtin_elementwise_fma(x2, w2v, z2); } }
;         pf[j] = log_sigmoid_fast(z2[0]) * (1.0f / 16.0f); sb[j] = log_sigmoid_fast(z2[1]) * (1.0f / 16.0f);
	v_mov_b32_e32 v134, v110
	s_andn2_b64 vcc, exec, s[52:53]
	s_waitcnt lgkmcnt(0)
	v_mov_b32_e32 v135, v130
	v_mov_b32_e32 v130, v111
	s_waitcnt vmcnt(0)
	v_pk_fma_f32 v[134:135], v[134:135], v[76:77], v[108:109]
	s_nop 0
	v_pk_fma_f32 v[110:111], v[130:131], v[90:91], v[134:135]
	v_mov_b32_e32 v130, v112
	v_mov_b32_e32 v131, v132
	v_pk_fma_f32 v[110:111], v[130:131], v[88:89], v[110:111]
	v_mov_b32_e32 v132, v113
	v_pk_fma_f32 v[130:131], v[132:133], v[86:87], v[110:111]
	ds_read_b128 v[110:113], v127 offset:36944
	v_mov_b32_e32 v132, v114
	v_mov_b32_e32 v114, v116
	v_mov_b32_e32 v116, v118
	s_waitcnt lgkmcnt(0)
	v_mov_b32_e32 v133, v110
	v_pk_fma_f32 v[130:131], v[132:133], v[98:99], v[130:131]
	v_mov_b32_e32 v110, v115
	v_pk_fma_f32 v[110:111], v[110:111], v[94:95], v[130:131]
	v_mov_b32_e32 v115, v112
	v_pk_fma_f32 v[110:111], v[114:115], v[96:97], v[110:111]
	v_mov_b32_e32 v112, v117
	v_pk_fma_f32 v[114:115], v[112:113], v[100:101], v[110:111]
	ds_read_b128 v[110:113], v127 offset:36960
	s_waitcnt lgkmcnt(0)
	v_mov_b32_e32 v117, v110
	v_pk_fma_f32 v[114:115], v[116:117], v[92:93], v[114:115]
	v_mov_b32_e32 v110, v119
	v_pk_fma_f32 v[110:111], v[110:111], v[102:103], v[114:115]
	v_mov_b32_e32 v114, v120
	v_mov_b32_e32 v115, v112
	v_pk_fma_f32 v[110:111], v[114:115], v[104:105], v[110:111]
	v_mov_b32_e32 v112, v121
	v_pk_fma_f32 v[114:115], v[112:113], v[106:107], v[110:111]
	ds_read_b128 v[110:113], v127 offset:36976
	v_mov_b32_e32 v116, v122
	s_waitcnt lgkmcnt(0)
	v_mov_b32_e32 v117, v110
	v_pk_fma_f32 v[114:115], v[116:117], v[84:85], v[114:115]
	v_mov_b32_e32 v110, v123
	v_pk_fma_f32 v[110:111], v[110:111], v[82:83], v[114:115]
	v_mov_b32_e32 v114, v124
	v_mov_b32_e32 v115, v112
	v_pk_fma_f32 v[110:111], v[114:115], v[80:81], v[110:111]
	ds_read_b128 v[114:117], v127 offset:36992
	ds_read_b128 v[118:121], v127 offset:37056
	v_mov_b32_e32 v112, v125
	v_pk_fma_f32 v[110:111], v[112:113], v[78:79], v[110:111]
	s_waitcnt lgkmcnt(1)
	v_mov_b32_e32 v122, v114
	s_waitcnt lgkmcnt(0)
	v_mov_b32_e32 v123, v118
	v_pk_fma_f32 v[122:123], v[122:123], v[76:77], v[108:109]
	v_mov_b32_e32 v118, v115
	v_pk_fma_f32 v[114:115], v[118:119], v[90:91], v[122:123]
	v_mov_b32_e32 v118, v116
	v_mov_b32_e32 v119, v120
	v_pk_fma_f32 v[114:115], v[118:119], v[88:89], v[114:115]
	v_mov_b32_e32 v120, v117
	v_pk_fma_f32 v[114:115], v[120:121], v[86:87], v[114:115]
	ds_read_b128 v[116:119], v127 offset:37008
	ds_read_b128 v[120:123], v127 offset:37072
	v_mul_f32_e64 v59, |v110|, s93
	v_exp_f32_e32 v59, v59
	v_min_f32_e32 v110, 0, v110
	s_waitcnt lgkmcnt(1)
	v_mov_b32_e32 v124, v116
	s_waitcnt lgkmcnt(0)
	v_mov_b32_e32 v125, v120
	v_pk_fma_f32 v[114:115], v[124:125], v[98:99], v[114:115]
	v_mov_b32_e32 v120, v117
	v_pk_fma_f32 v[114:115], v[120:121], v[94:95], v[114:115]
	v_mov_b32_e32 v116, v118
	v_mov_b32_e32 v117, v122
	v_pk_fma_f32 v[114:115], v[116:117], v[96:97], v[114:115]
	v_mov_b32_e32 v122, v119
	v_pk_fma_f32 v[122:123], v[122:123], v[100:101], v[114:115]
	ds_read_b128 v[114:117], v127 offset:37024
	ds_read_b128 v[118:121], v127 offset:37088
	v_add_f32_e32 v59, 1.0, v59
	v_log_f32_e32 v112, v59
	v_mul_f32_e64 v59, |v111|, s93
	s_waitcnt lgkmcnt(1)
	v_mov_b32_e32 v124, v114
	s_waitcnt lgkmcnt(0)
	v_mov_b32_e32 v125, v118
	v_pk_fma_f32 v[122:123], v[124:125], v[92:93], v[122:123]
	v_mov_b32_e32 v118, v115
	v_pk_fma_f32 v[114:115], v[118:119], v[102:103], v[122:123]
	v_mov_b32_e32 v118, v116
	v_mov_b32_e32 v119, v120
	v_pk_fma_f32 v[114:115], v[118:119], v[104:105], v[114:115]
	v_mov_b32_e32 v120, v117
	v_pk_fma_f32 v[122:123], v[120:121], v[106:107], v[114:115]
	ds_read_b128 v[114:117], v127 offset:37040
	ds_read_b128 v[118:121], v127 offset:37104
	v_exp_f32_e32 v61, v59
	v_min_f32_e32 v59, 0, v111
	s_waitcnt lgkmcnt(1)
	v_mov_b32_e32 v124, v114
	v_add_f32_e32 v61, 1.0, v61
	s_waitcnt lgkmcnt(0)
	v_mov_b32_e32 v125, v118
	v_log_f32_e32 v61, v61
	v_pk_fma_f32 v[122:123], v[124:125], v[84:85], v[122:123]
	v_mov_b32_e32 v118, v115
	v_pk_fma_f32 v[114:115], v[118:119], v[82:83], v[122:123]
	v_mov_b32_e32 v118, v116
	v_mov_b32_e32 v119, v120
	v_pk_fma_f32 v[114:115], v[118:119], v[80:81], v[114:115]
	v_mov_b32_e32 v120, v117
	v_pk_fma_f32 v[114:115], v[120:121], v[78:79], v[114:115]
	v_fmac_f32_e32 v59, 0xbf317218, v61
	v_mul_f32_e64 v61, |v114|, s93
	v_exp_f32_e32 v61, v61
	v_min_f32_e32 v111, 0, v114
	v_add_f32_e32 v61, 1.0, v61
	v_log_f32_e32 v113, v61
	v_mul_f32_e64 v61, |v115|, s93
	v_exp_f32_e32 v63, v61
	v_min_f32_e32 v61, 0, v115
	ds_read_b128 v[114:117], v127 offset:37120
	ds_read_b128 v[118:121], v127 offset:37184
	v_pk_fma_f32 v[110:111], v[112:113], s[10:11], v[110:111] op_sel_hi:[1,0,1]
	v_add_f32_e32 v63, 1.0, v63
	v_log_f32_e32 v112, v63
	s_waitcnt lgkmcnt(1)
	v_mov_b32_e32 v122, v114
	s_waitcnt lgkmcnt(0)
	v_mov_b32_e32 v123, v118
	v_pk_fma_f32 v[122:123], v[122:123], v[76:77], v[108:109]
	v_mov_b32_e32 v118, v115
	v_pk_fma_f32 v[114:115], v[118:119], v[90:91], v[122:123]
	v_mov_b32_e32 v118, v116
	v_mov_b32_e32 v119, v120
	v_pk_fma_f32 v[114:115], v[118:119], v[88:89], v[114:115]
	v_mov_b32_e32 v120, v117
	v_pk_fma_f32 v[122:123], v[120:121], v[86:87], v[114:115]
	ds_read_b128 v[114:117], v127 offset:37136
	ds_read_b128 v[118:121], v127 offset:37200
	v_pk_mul_f32 v[110:111], v[110:111], s[4:5] op_sel_hi:[1,0]
	v_readlane_b32 s4, v254, 13
	v_readlane_b32 s5, v254, 14
	s_waitcnt lgkmcnt(1)
	v_mov_b32_e32 v124, v114
	s_waitcnt lgkmcnt(0)
; #define LAS __attribute__((address_space(3)))
; __device__ __forceinline__ float log_sigmoid_fast(float z) {
;     const float e = __builtin_amdgcn_exp2f(-1.44269504088896f * fabsf(z));
;     return fminf(z, 0.f) - 0.693147180559945f * __builtin_amdgcn_logf(1.0f + e);
; }
; __device__ __forceinline__ void gla_gates(const LAS float* lrs, const float* w2, const float* gbias, int h, int d, int w, float (&pf)[16], float (&sb)[16]) {
;     ...
; #pragma unroll
;     for (int j = 0; j < 16; ++j) {
;         const LAS float* lr = lrs + (w * 16 + j) * 32;
;         f32x2_t z2 = {bf, bb};
; #pragma unroll
;         for (int r4 = 0; r4 < 4; ++r4) { const f32x4 a = *(const LAS f32x4*)(lr + 4 * r4), b = *(const LAS f32x4*)(lr + 16 + 4 * r4);
; #pragma unroll
;             for (int q = 0; q < 4; ++q) { const f32x2_t x2 = {a[q], b[q]}, w2v = {wf[4 * r4 + q], wb[4 * r4 + q]}; z2 = __builtin_elementwise_fma(x2, w2v, z2); } }
;         pf[j] = log_sigmoid_fast(z2[0]) * (1.0f / 16.0f); sb[j] = log_sigmoid_fast(z2[1]) * (1.0f / 16.0f);
	v_mov_b32_e32 v125, v118
	v_pk_fma_f32 v[122:123], v[124:125], v[98:99], v[122:123]
	v_mov_b32_e32 v118, v115
	v_pk_fma_f32 v[114:115], v[118:119], v[94:95], v[122:123]
	v_mov_b32_e32 v118, v116
	v_mov_b32_e32 v119, v120
	v_pk_fma_f32 v[114:115], v[118:119], v[96:97], v[114:115]
	v_mov_b32_e32 v120, v117
	v_pk_fma_f32 v[122:123], v[120:121], v[100:101], v[114:115]
	ds_read_b128 v[114:117], v127 offset:37152
	ds_read_b128 v[118:121], v127 offset:37216
	s_mov_b64 s[10:11], -1
	s_waitcnt lgkmcnt(1)
	v_mov_b32_e32 v124, v114
	s_waitcnt lgkmcnt(0)
	v_mov_b32_e32 v125, v118
	v_pk_fma_f32 v[122:123], v[124:125], v[92:93], v[122:123]
	v_mov_b32_e32 v118, v115
	v_pk_fma_f32 v[114:115], v[118:119], v[102:103], v[122:123]
	v_mov_b32_e32 v118, v116
	v_mov_b32_e32 v119, v120
	v_pk_fma_f32 v[114:115], v[118:119], v[104:105], v[114:115]
	v_mov_b32_e32 v120, v117
	v_pk_fma_f32 v[122:123], v[120:121], v[106:107], v[114:115]
	ds_read_b128 v[114:117], v127 offset:37168
	ds_read_b128 v[118:121], v127 offset:37232
	s_waitcnt lgkmcnt(1)
	v_mov_b32_e32 v124, v114
	s_waitcnt lgkmcnt(0)
	v_mov_b32_e32 v125, v118
	v_pk_fma_f32 v[122:123], v[124:125], v[84:85], v[122:123]
	v_mov_b32_e32 v118, v115
	v_pk_fma_f32 v[114:115], v[118:119], v[82:83], v[122:123]
	v_mov_b32_e32 v118, v116
	v_mov_b32_e32 v119, v120
	v_pk_fma_f32 v[114:115], v[118:119], v[80:81], v[114:115]
	v_mov_b32_e32 v120, v117
	v_pk_fma_f32 v[114:115], v[120:121], v[78:79], v[114:115]
	s_nop 0
	v_mul_f32_e64 v63, |v114|, s93
	v_exp_f32_e32 v65, v63
	v_min_f32_e32 v63, 0, v114
	v_min_f32_e32 v113, 0, v115
	v_add_f32_e32 v65, 1.0, v65
	v_log_f32_e32 v65, v65
	s_nop 0
	v_fmac_f32_e32 v63, 0xbf317218, v65
	v_mul_f32_e64 v65, |v115|, s93
	ds_read_b128 v[114:117], v127 offset:37248
	ds_read_b128 v[118:121], v127 offset:37312
	v_exp_f32_e32 v65, v65
	s_waitcnt lgkmcnt(1)
	v_mov_b32_e32 v122, v114
	s_waitcnt lgkmcnt(0)
	v_mov_b32_e32 v123, v118
	v_pk_fma_f32 v[122:123], v[122:123], v[76:77], v[108:109]
	v_mov_b32_e32 v118, v115
	v_pk_fma_f32 v[114:115], v[118:119], v[90:91], v[122:123]
	v_mov_b32_e32 v118, v116
	v_mov_b32_e32 v119, v120
	v_pk_fma_f32 v[114:115], v[118:119], v[88:89], v[114:115]
	v_mov_b32_e32 v120, v117
	v_pk_fma_f32 v[122:123], v[120:121], v[86:87], v[114:115]
	ds_read_b128 v[114:117], v127 offset:37264
	ds_read_b128 v[118:121], v127 offset:37328
	v_add_f32_e32 v65, 1.0, v65
	v_log_f32_e32 v65, v65
	s_waitcnt lgkmcnt(1)
	v_mov_b32_e32 v124, v114
	s_waitcnt lgkmcnt(0)
	v_mov_b32_e32 v125, v118
	v_pk_fma_f32 v[122:123], v[124:125], v[98:99], v[122:123]
	v_mov_b32_e32 v118, v115
	v_pk_fma_f32 v[114:115], v[118:119], v[94:95], v[122:123]
	v_mov_b32_e32 v118, v116
	v_mov_b32_e32 v119, v120
	v_pk_fma_f32 v[114:115], v[118:119], v[96:97], v[114:115]
	v_mov_b32_e32 v120, v117
	v_pk_fma_f32 v[122:123], v[120:121], v[100:101], v[114:115]
	ds_read_b128 v[114:117], v127 offset:37280
	ds_read_b128 v[118:121], v127 offset:37344
	v_fmac_f32_e32 v113, 0xbf317218, v65
	s_waitcnt lgkmcnt(1)
	v_mov_b32_e32 v124, v114
	s_waitcnt lgkmcnt(0)
	v_mov_b32_e32 v125, v118
	v_pk_fma_f32 v[122:123], v[124:125], v[92:93], v[122:123]
	v_mov_b32_e32 v118, v115
	v_pk_fma_f32 v[114:115], v[118:119], v[102:103], v[122:123]
	v_mov_b32_e32 v118, v116
	v_mov_b32_e32 v119, v120
	v_pk_fma_f32 v[114:115], v[118:119], v[104:105], v[114:115]
	v_mov_b32_e32 v120, v117
	v_pk_fma_f32 v[122:123], v[120:121], v[106:107], v[114:115]
	ds_read_b128 v[114:117], v127 offset:37296
	ds_read_b128 v[118:121], v127 offset:37360
	s_waitcnt lgkmcnt(1)
	v_mov_b32_e32 v124, v114
	s_waitcnt lgkmcnt(0)
	v_mov_b32_e32 v125, v118
	v_pk_fma_f32 v[122:123], v[124:125], v[84:85], v[122:123]
	v_mov_b32_e32 v118, v115
	v_pk_fma_f32 v[114:115], v[118:119], v[82:83], v[122:123]
	v_mov_b32_e32 v118, v116
	v_mov_b32_e32 v119, v120
	v_pk_fma_f32 v[114:115], v[118:119], v[80:81], v[114:115]
	v_mov_b32_e32 v120, v117
	v_pk_fma_f32 v[114:115], v[120:121], v[78:79], v[114:115]
	ds_read_b128 v[116:119], v127 offset:37376
	ds_read_b128 v[120:123], v127 offset:37440
	v_mul_f32_e64 v65, |v114|, s93
	v_exp_f32_e32 v67, v65
	v_min_f32_e32 v65, 0, v114
	s_waitcnt lgkmcnt(1)
	v_mov_b32_e32 v124, v116
	s_waitcnt lgkmcnt(0)
	v_mov_b32_e32 v125, v120
	v_pk_fma_f32 v[124:125], v[124:125], v[76:77], v[108:109]
	v_mov_b32_e32 v120, v117
	v_pk_fma_f32 v[116:117], v[120:121], v[90:91], v[124:125]
	v_mov_b32_e32 v120, v118
	v_mov_b32_e32 v121, v122
	v_pk_fma_f32 v[116:117], v[120:121], v[88:89], v[116:117]
	v_mov_b32_e32 v122, v119
	v_pk_fma_f32 v[124:125], v[122:123], v[86:87], v[116:117]
	ds_read_b128 v[116:119], v127 offset:37392
	ds_read_b128 v[120:123], v127 offset:37456
	v_add_f32_e32 v67, 1.0, v67
	v_log_f32_e32 v67, v67
	s_waitcnt lgkmcnt(1)
	v_mov_b32_e32 v130, v116
	s_waitcnt lgkmcnt(0)
	v_mov_b32_e32 v131, v120
	v_pk_fma_f32 v[124:125], v[130:131], v[98:99], v[124:125]
	v_mov_b32_e32 v120, v117
	v_pk_fma_f32 v[116:117], v[120:121], v[94:95], v[124:125]
	v_mov_b32_e32 v120, v118
	v_mov_b32_e32 v121, v122
	v_pk_fma_f32 v[116:117], v[120:121], v[96:97], v[116:117]
	v_mov_b32_e32 v122, v119
	v_pk_fma_f32 v[124:125], v[122:123], v[100:101], v[116:117]
	ds_read_b128 v[116:119], v127 offset:37408
	ds_read_b128 v[120:123], v127 offset:37472
	v_fmac_f32_e32 v65, 0xbf317218, v67
	v_mul_f32_e64 v67, |v115|, s93
	v_exp_f32_e32 v69, v67
	s_waitcnt lgkmcnt(1)
	v_mov_b32_e32 v130, v116
	s_waitcnt lgkmcnt(0)
	v_mov_b32_e32 v131, v120
	v_pk_fma_f32 v[124:125], v[130:131], v[92:93], v[124:125]
	v_mov_b32_e32 v120, v117
	v_pk_fma_f32 v[116:117], v[120:121], v[102:103], v[124:125]
	v_mov_b32_e32 v120, v118
	v_mov_b32_e32 v121, v122
	v_pk_fma_f32 v[116:117], v[120:121], v[104:105], v[116:117]
	v_mov_b32_e32 v122, v119
	v_pk_fma_f32 v[124:125], v[122:123], v[106:107], v[116:117]
	ds_read_b128 v[116:119], v127 offset:37424
	ds_read_b128 v[120:123], v127 offset:37488
	v_add_f32_e32 v69, 1.0, v69
	v_log_f32_e32 v114, v69
	v_min_f32_e32 v67, 0, v115
	s_waitcnt lgkmcnt(1)
; #define LAS __attribute__((address_space(3)))
; __device__ __forceinline__ float log_sigmoid_fast(float z) {
;     const float e = __builtin_amdgcn_exp2f(-1.44269504088896f * fabsf(z));
;     return fminf(z, 0.f) - 0.693147180559945f * __builtin_amdgcn_logf(1.0f + e);
; }
; __device__ __forceinline__ void gla_gates(const LAS float* lrs, const float* w2, const float* gbias, int h, int d, int w, float (&pf)[16], float (&sb)[16]) {
;     ...
; #pragma unroll
;     for (int j = 0; j < 16; ++j) {
;         const LAS float* lr = lrs + (w * 16 + j) * 32;
;         f32x2_t z2 = {bf, bb};
; #pragma unroll
;         for (int r4 = 0; r4 < 4; ++r4) { const f32x4 a = *(const LAS f32x4*)(lr + 4 * r4), b = *(const LAS f32x4*)(lr + 16 + 4 * r4);
; #pragma unroll
;             for (int q = 0; q < 4; ++q) { const f32x2_t x2 = {a[q], b[q]}, w2v = {wf[4 * r4 + q], wb[4 * r4 + q]}; z2 = __builtin_elementwise_fma(x2, w2v, z2); } }
;         pf[j] = log_sigmoid_fast(z2[0]) * (1.0f / 16.0f); sb[j] = log_sigmoid_fast(z2[1]) * (1.0f / 16.0f);
	v_mov_b32_e32 v130, v116
	s_waitcnt lgkmcnt(0)
	v_mov_b32_e32 v131, v120
	v_pk_fma_f32 v[124:125], v[130:131], v[84:85], v[124:125]
	v_mov_b32_e32 v120, v117
	v_pk_fma_f32 v[116:117], v[120:121], v[82:83], v[124:125]
	v_mov_b32_e32 v120, v118
	v_mov_b32_e32 v121, v122
	v_pk_fma_f32 v[116:117], v[120:121], v[80:81], v[116:117]
	v_mov_b32_e32 v122, v119
	v_pk_fma_f32 v[116:117], v[122:123], v[78:79], v[116:117]
	s_nop 0
	v_mul_f32_e64 v69, |v116|, s93
	v_exp_f32_e32 v71, v69
	v_min_f32_e32 v69, 0, v116
	v_min_f32_e32 v115, 0, v117
	v_add_f32_e32 v71, 1.0, v71
	v_log_f32_e32 v71, v71
	s_nop 0
	v_fmac_f32_e32 v69, 0xbf317218, v71
	v_mul_f32_e64 v71, |v117|, s93
	ds_read_b128 v[116:119], v127 offset:37504
	ds_read_b128 v[120:123], v127 offset:37568
	v_exp_f32_e32 v71, v71
	s_waitcnt lgkmcnt(1)
	v_mov_b32_e32 v124, v116
	s_waitcnt lgkmcnt(0)
	v_mov_b32_e32 v125, v120
	v_pk_fma_f32 v[124:125], v[124:125], v[76:77], v[108:109]
	v_mov_b32_e32 v120, v117
	v_pk_fma_f32 v[116:117], v[120:121], v[90:91], v[124:125]
	v_mov_b32_e32 v120, v118
	v_mov_b32_e32 v121, v122
	v_pk_fma_f32 v[116:117], v[120:121], v[88:89], v[116:117]
	v_mov_b32_e32 v122, v119
	v_pk_fma_f32 v[124:125], v[122:123], v[86:87], v[116:117]
	ds_read_b128 v[116:119], v127 offset:37520
	ds_read_b128 v[120:123], v127 offset:37584
	v_add_f32_e32 v71, 1.0, v71
	v_log_f32_e32 v71, v71
	s_waitcnt lgkmcnt(1)
	v_mov_b32_e32 v130, v116
	s_waitcnt lgkmcnt(0)
	v_mov_b32_e32 v131, v120
	v_pk_fma_f32 v[124:125], v[130:131], v[98:99], v[124:125]
	v_mov_b32_e32 v120, v117
	v_pk_fma_f32 v[116:117], v[120:121], v[94:95], v[124:125]
	v_mov_b32_e32 v120, v118
	v_mov_b32_e32 v121, v122
	v_pk_fma_f32 v[116:117], v[120:121], v[96:97], v[116:117]
	v_mov_b32_e32 v122, v119
	v_pk_fma_f32 v[124:125], v[122:123], v[100:101], v[116:117]
	ds_read_b128 v[116:119], v127 offset:37536
	ds_read_b128 v[120:123], v127 offset:37600
	v_fmac_f32_e32 v115, 0xbf317218, v71
	s_waitcnt lgkmcnt(1)
	v_mov_b32_e32 v130, v116
	s_waitcnt lgkmcnt(0)
	v_mov_b32_e32 v131, v120
	v_pk_fma_f32 v[124:125], v[130:131], v[92:93], v[124:125]
	v_mov_b32_e32 v120, v117
	v_pk_fma_f32 v[116:117], v[120:121], v[102:103], v[124:125]
	v_mov_b32_e32 v120, v118
	v_mov_b32_e32 v121, v122
	v_pk_fma_f32 v[116:117], v[120:121], v[104:105], v[116:117]
	v_mov_b32_e32 v122, v119
	v_pk_fma_f32 v[124:125], v[122:123], v[106:107], v[116:117]
	ds_read_b128 v[116:119], v127 offset:37552
	ds_read_b128 v[120:123], v127 offset:37616
	s_waitcnt lgkmcnt(1)
	v_mov_b32_e32 v130, v116
	s_waitcnt lgkmcnt(0)
	v_mov_b32_e32 v131, v120
	v_pk_fma_f32 v[124:125], v[130:131], v[84:85], v[124:125]
	v_mov_b32_e32 v120, v117
	v_pk_fma_f32 v[116:117], v[120:121], v[82:83], v[124:125]
	v_mov_b32_e32 v120, v118
	v_mov_b32_e32 v121, v122
	v_pk_fma_f32 v[116:117], v[120:121], v[80:81], v[116:117]
	v_mov_b32_e32 v122, v119
	v_pk_fma_f32 v[116:117], v[122:123], v[78:79], v[116:117]
	ds_read_b128 v[118:121], v127 offset:37632
	ds_read_b128 v[122:125], v127 offset:37696
	v_mul_f32_e64 v71, |v116|, s93
	v_exp_f32_e32 v73, v71
	v_min_f32_e32 v71, 0, v116
	s_waitcnt lgkmcnt(1)
	v_mov_b32_e32 v130, v118
	s_waitcnt lgkmcnt(0)
	v_mov_b32_e32 v131, v122
	v_pk_fma_f32 v[130:131], v[130:131], v[76:77], v[108:109]
	v_mov_b32_e32 v122, v119
	v_pk_fma_f32 v[118:119], v[122:123], v[90:91], v[130:131]
	v_mov_b32_e32 v122, v120
	v_mov_b32_e32 v123, v124
	v_pk_fma_f32 v[118:119], v[122:123], v[88:89], v[118:119]
	v_mov_b32_e32 v124, v121
	v_pk_fma_f32 v[130:131], v[124:125], v[86:87], v[118:119]
	ds_read_b128 v[118:121], v127 offset:37648
	ds_read_b128 v[122:125], v127 offset:37712
	v_add_f32_e32 v73, 1.0, v73
	v_log_f32_e32 v73, v73
	s_waitcnt lgkmcnt(1)
	v_mov_b32_e32 v132, v118
	s_waitcnt lgkmcnt(0)
	v_mov_b32_e32 v133, v122
	v_pk_fma_f32 v[130:131], v[132:133], v[98:99], v[130:131]
	v_mov_b32_e32 v122, v119
	v_pk_fma_f32 v[118:119], v[122:123], v[94:95], v[130:131]
	v_mov_b32_e32 v122, v120
	v_mov_b32_e32 v123, v124
	v_pk_fma_f32 v[118:119], v[122:123], v[96:97], v[118:119]
	v_mov_b32_e32 v124, v121
	v_pk_fma_f32 v[130:131], v[124:125], v[100:101], v[118:119]
	ds_read_b128 v[118:121], v127 offset:37664
	ds_read_b128 v[122:125], v127 offset:37728
	v_fmac_f32_e32 v71, 0xbf317218, v73
	v_mul_f32_e64 v73, |v117|, s93
	v_exp_f32_e32 v75, v73
	s_waitcnt lgkmcnt(1)
	v_mov_b32_e32 v132, v118
	s_waitcnt lgkmcnt(0)
	v_mov_b32_e32 v133, v122
	v_pk_fma_f32 v[130:131], v[132:133], v[92:93], v[130:131]
	v_mov_b32_e32 v122, v119
	v_pk_fma_f32 v[118:119], v[122:123], v[102:103], v[130:131]
	v_mov_b32_e32 v122, v120
	v_mov_b32_e32 v123, v124
	v_pk_fma_f32 v[118:119], v[122:123], v[104:105], v[118:119]
	v_mov_b32_e32 v124, v121
	v_pk_fma_f32 v[130:131], v[124:125], v[106:107], v[118:119]
	ds_read_b128 v[118:121], v127 offset:37680
	ds_read_b128 v[122:125], v127 offset:37744
	v_add_f32_e32 v75, 1.0, v75
	v_log_f32_e32 v116, v75
	v_min_f32_e32 v73, 0, v117
	s_waitcnt lgkmcnt(1)
	v_mov_b32_e32 v132, v118
	s_waitcnt lgkmcnt(0)
	v_mov_b32_e32 v133, v122
	v_pk_fma_f32 v[130:131], v[132:133], v[84:85], v[130:131]
	v_mov_b32_e32 v122, v119
	v_pk_fma_f32 v[118:119], v[122:123], v[82:83], v[130:131]
	v_mov_b32_e32 v122, v120
	v_mov_b32_e32 v123, v124
	v_pk_fma_f32 v[118:119], v[122:123], v[80:81], v[118:119]
	v_mov_b32_e32 v124, v121
	v_pk_fma_f32 v[118:119], v[124:125], v[78:79], v[118:119]
	s_nop 0
	v_mul_f32_e64 v75, |v118|, s93
	v_exp_f32_e32 v117, v75
	v_min_f32_e32 v75, 0, v118
	v_add_f32_e32 v117, 1.0, v117
	v_log_f32_e32 v117, v117
	s_nop 0
	v_fmac_f32_e32 v75, 0xbf317218, v117
	v_mul_f32_e64 v117, |v119|, s93
	v_exp_f32_e32 v118, v117
	v_min_f32_e32 v117, 0, v119
	v_add_f32_e32 v118, 1.0, v118
	v_log_f32_e32 v118, v118
	s_nop 0
	v_fmac_f32_e32 v117, 0xbf317218, v118
	ds_read_b128 v[118:121], v127 offset:37760
	ds_read_b128 v[122:125], v127 offset:37824
	s_waitcnt lgkmcnt(1)
; #define LAS __attribute__((address_space(3)))
; __device__ __forceinline__ float log_sigmoid_fast(float z) {
;     const float e = __builtin_amdgcn_exp2f(-1.44269504088896f * fabsf(z));
;     return fminf(z, 0.f) - 0.693147180559945f * __builtin_amdgcn_logf(1.0f + e);
; }
; __device__ __forceinline__ void gla_gates(const LAS float* lrs, const float* w2, const float* gbias, int h, int d, int w, float (&pf)[16], float (&sb)[16]) {
;     ...
; #pragma unroll
;     for (int j = 0; j < 16; ++j) {
;         const LAS float* lr = lrs + (w * 16 + j) * 32;
;         f32x2_t z2 = {bf, bb};
; #pragma unroll
;         for (int r4 = 0; r4 < 4; ++r4) { const f32x4 a = *(const LAS f32x4*)(lr + 4 * r4), b = *(const LAS f32x4*)(lr + 16 + 4 * r4);
; #pragma unroll
;             for (int q = 0; q < 4; ++q) { const f32x2_t x2 = {a[q], b[q]}, w2v = {wf[4 * r4 + q], wb[4 * r4 + q]}; z2 = __builtin_elementwise_fma(x2, w2v, z2); } }
;         pf[j] = log_sigmoid_fast(z2[0]) * (1.0f / 16.0f); sb[j] = log_sigmoid_fast(z2[1]) * (1.0f / 16.0f);
	v_mov_b32_e32 v130, v118
	s_waitcnt lgkmcnt(0)
	v_mov_b32_e32 v131, v122
	v_pk_fma_f32 v[130:131], v[130:131], v[76:77], v[108:109]
	v_mov_b32_e32 v122, v119
	v_pk_fma_f32 v[118:119], v[122:123], v[90:91], v[130:131]
	v_mov_b32_e32 v122, v120
	v_mov_b32_e32 v123, v124
	v_pk_fma_f32 v[118:119], v[122:123], v[88:89], v[118:119]
	v_mov_b32_e32 v124, v121
	v_pk_fma_f32 v[130:131], v[124:125], v[86:87], v[118:119]
	ds_read_b128 v[118:121], v127 offset:37776
	ds_read_b128 v[122:125], v127 offset:37840
	s_waitcnt lgkmcnt(1)
	v_mov_b32_e32 v132, v118
	s_waitcnt lgkmcnt(0)
	v_mov_b32_e32 v133, v122
	v_pk_fma_f32 v[130:131], v[132:133], v[98:99], v[130:131]
	v_mov_b32_e32 v122, v119
	v_pk_fma_f32 v[118:119], v[122:123], v[94:95], v[130:131]
	v_mov_b32_e32 v122, v120
	v_mov_b32_e32 v123, v124
	v_pk_fma_f32 v[118:119], v[122:123], v[96:97], v[118:119]
	v_mov_b32_e32 v124, v121
	v_pk_fma_f32 v[130:131], v[124:125], v[100:101], v[118:119]
	ds_read_b128 v[118:121], v127 offset:37792
	ds_read_b128 v[122:125], v127 offset:37856
	s_waitcnt lgkmcnt(1)
	v_mov_b32_e32 v132, v118
	s_waitcnt lgkmcnt(0)
	v_mov_b32_e32 v133, v122
	v_pk_fma_f32 v[130:131], v[132:133], v[92:93], v[130:131]
	v_mov_b32_e32 v122, v119
	v_pk_fma_f32 v[118:119], v[122:123], v[102:103], v[130:131]
	v_mov_b32_e32 v122, v120
	v_mov_b32_e32 v123, v124
	v_pk_fma_f32 v[118:119], v[122:123], v[104:105], v[118:119]
	v_mov_b32_e32 v124, v121
	v_pk_fma_f32 v[130:131], v[124:125], v[106:107], v[118:119]
	ds_read_b128 v[118:121], v127 offset:37808
	ds_read_b128 v[122:125], v127 offset:37872
	s_waitcnt lgkmcnt(1)
	v_mov_b32_e32 v132, v118
	s_waitcnt lgkmcnt(0)
	v_mov_b32_e32 v133, v122
	v_pk_fma_f32 v[130:131], v[132:133], v[84:85], v[130:131]
	v_mov_b32_e32 v122, v119
	v_pk_fma_f32 v[118:119], v[122:123], v[82:83], v[130:131]
	v_mov_b32_e32 v122, v120
	v_mov_b32_e32 v123, v124
	v_pk_fma_f32 v[118:119], v[122:123], v[80:81], v[118:119]
	v_mov_b32_e32 v124, v121
	v_pk_fma_f32 v[118:119], v[124:125], v[78:79], v[118:119]
	s_nop 0
	v_mul_f32_e64 v120, |v118|, s93
	v_exp_f32_e32 v120, v120
	v_min_f32_e32 v130, 0, v118
	v_min_f32_e32 v131, 0, v119
	v_add_f32_e32 v118, 1.0, v120
	ds_read_b128 v[120:123], v127 offset:37888
	ds_read_b128 v[132:135], v127 offset:37952
	v_log_f32_e32 v118, v118
	s_waitcnt lgkmcnt(1)
	v_mov_b32_e32 v124, v120
	s_waitcnt lgkmcnt(0)
	v_mov_b32_e32 v125, v132
	v_pk_fma_f32 v[124:125], v[124:125], v[76:77], v[108:109]
	v_mov_b32_e32 v132, v121
	v_pk_fma_f32 v[120:121], v[132:133], v[90:91], v[124:125]
	v_mov_b32_e32 v124, v122
	v_mov_b32_e32 v125, v134
	v_pk_fma_f32 v[120:121], v[124:125], v[88:89], v[120:121]
	v_mov_b32_e32 v134, v123
	v_pk_fma_f32 v[124:125], v[134:135], v[86:87], v[120:121]
	ds_read_b128 v[120:123], v127 offset:37904
	ds_read_b128 v[132:135], v127 offset:37968
	v_fmac_f32_e32 v130, 0xbf317218, v118
	v_mul_f32_e64 v118, |v119|, s93
	v_exp_f32_e32 v118, v118
	s_waitcnt lgkmcnt(1)
	v_mov_b32_e32 v136, v120
	s_waitcnt lgkmcnt(0)
	v_mov_b32_e32 v137, v132
	v_pk_fma_f32 v[124:125], v[136:137], v[98:99], v[124:125]
	v_mov_b32_e32 v132, v121
	v_pk_fma_f32 v[120:121], v[132:133], v[94:95], v[124:125]
	v_mov_b32_e32 v124, v122
	v_mov_b32_e32 v125, v134
	v_pk_fma_f32 v[120:121], v[124:125], v[96:97], v[120:121]
	v_mov_b32_e32 v134, v123
	v_pk_fma_f32 v[124:125], v[134:135], v[100:101], v[120:121]
	ds_read_b128 v[120:123], v127 offset:37920
	ds_read_b128 v[132:135], v127 offset:37984
	v_add_f32_e32 v118, 1.0, v118
	v_log_f32_e32 v118, v118
	s_waitcnt lgkmcnt(1)
	v_mov_b32_e32 v136, v120
	s_waitcnt lgkmcnt(0)
	v_mov_b32_e32 v137, v132
	v_pk_fma_f32 v[124:125], v[136:137], v[92:93], v[124:125]
	v_mov_b32_e32 v132, v121
	v_pk_fma_f32 v[120:121], v[132:133], v[102:103], v[124:125]
	v_mov_b32_e32 v124, v122
	v_mov_b32_e32 v125, v134
	v_pk_fma_f32 v[120:121], v[124:125], v[104:105], v[120:121]
	v_mov_b32_e32 v134, v123
	v_pk_fma_f32 v[124:125], v[134:135], v[106:107], v[120:121]
	ds_read_b128 v[120:123], v127 offset:37936
	ds_read_b128 v[132:135], v127 offset:38000
	s_waitcnt lgkmcnt(1)
	v_mov_b32_e32 v136, v120
	s_waitcnt lgkmcnt(0)
	v_mov_b32_e32 v137, v132
	v_pk_fma_f32 v[124:125], v[136:137], v[84:85], v[124:125]
	v_mov_b32_e32 v132, v121
	v_pk_fma_f32 v[120:121], v[132:133], v[82:83], v[124:125]
	v_mov_b32_e32 v124, v122
	v_mov_b32_e32 v125, v134
	v_pk_fma_f32 v[120:121], v[124:125], v[80:81], v[120:121]
	v_mov_b32_e32 v134, v123
	v_pk_fma_f32 v[120:121], v[134:135], v[78:79], v[120:121]
	s_nop 0
	v_mul_f32_e64 v119, |v120|, s93
	v_exp_f32_e32 v119, v119
	v_min_f32_e32 v132, 0, v120
	v_add_f32_e32 v119, 1.0, v119
	v_log_f32_e32 v119, v119
	s_nop 0
	v_fmac_f32_e32 v132, 0xbf317218, v119
	v_mul_f32_e64 v119, |v121|, s93
	v_exp_f32_e32 v120, v119
	v_min_f32_e32 v119, 0, v121
	v_add_f32_e32 v120, 1.0, v120
	v_log_f32_e32 v120, v120
	s_nop 0
	v_fmac_f32_e32 v119, 0xbf317218, v120
	ds_read_b128 v[120:123], v127 offset:38016
	ds_read_b128 v[134:137], v127 offset:38080
	s_waitcnt lgkmcnt(1)
	v_mov_b32_e32 v124, v120
	s_waitcnt lgkmcnt(0)
	v_mov_b32_e32 v125, v134
	v_pk_fma_f32 v[124:125], v[124:125], v[76:77], v[108:109]
	v_mov_b32_e32 v134, v121
	v_pk_fma_f32 v[120:121], v[134:135], v[90:91], v[124:125]
	v_mov_b32_e32 v124, v122
	v_mov_b32_e32 v125, v136
	v_pk_fma_f32 v[120:121], v[124:125], v[88:89], v[120:121]
	v_mov_b32_e32 v136, v123
	v_pk_fma_f32 v[124:125], v[136:137], v[86:87], v[120:121]
	ds_read_b128 v[120:123], v127 offset:38032
	ds_read_b128 v[134:137], v127 offset:38096
	s_waitcnt lgkmcnt(1)
	v_mov_b32_e32 v138, v120
	s_waitcnt lgkmcnt(0)
; #define LAS __attribute__((address_space(3)))
; __device__ __forceinline__ float log_sigmoid_fast(float z) {
;     const float e = __builtin_amdgcn_exp2f(-1.44269504088896f * fabsf(z));
;     return fminf(z, 0.f) - 0.693147180559945f * __builtin_amdgcn_logf(1.0f + e);
; }
; __device__ __forceinline__ void gla_gates(const LAS float* lrs, const float* w2, const float* gbias, int h, int d, int w, float (&pf)[16], float (&sb)[16]) {
;     ...
; #pragma unroll
;     for (int j = 0; j < 16; ++j) {
;         const LAS float* lr = lrs + (w * 16 + j) * 32;
;         f32x2_t z2 = {bf, bb};
; #pragma unroll
;         for (int r4 = 0; r4 < 4; ++r4) { const f32x4 a = *(const LAS f32x4*)(lr + 4 * r4), b = *(const LAS f32x4*)(lr + 16 + 4 * r4);
; #pragma unroll
;             for (int q = 0; q < 4; ++q) { const f32x2_t x2 = {a[q], b[q]}, w2v = {wf[4 * r4 + q], wb[4 * r4 + q]}; z2 = __builtin_elementwise_fma(x2, w2v, z2); } }
;         pf[j] = log_sigmoid_fast(z2[0]) * (1.0f / 16.0f); sb[j] = log_sigmoid_fast(z2[1]) * (1.0f / 16.0f);
	v_mov_b32_e32 v139, v134
	v_pk_fma_f32 v[124:125], v[138:139], v[98:99], v[124:125]
	v_mov_b32_e32 v134, v121
	v_pk_fma_f32 v[120:121], v[134:135], v[94:95], v[124:125]
	v_mov_b32_e32 v124, v122
	v_mov_b32_e32 v125, v136
	v_pk_fma_f32 v[120:121], v[124:125], v[96:97], v[120:121]
	v_mov_b32_e32 v136, v123
	v_pk_fma_f32 v[124:125], v[136:137], v[100:101], v[120:121]
	ds_read_b128 v[120:123], v127 offset:38048
	ds_read_b128 v[134:137], v127 offset:38112
	s_waitcnt lgkmcnt(1)
	v_mov_b32_e32 v138, v120
	s_waitcnt lgkmcnt(0)
	v_mov_b32_e32 v139, v134
	v_pk_fma_f32 v[124:125], v[138:139], v[92:93], v[124:125]
	v_mov_b32_e32 v134, v121
	v_pk_fma_f32 v[120:121], v[134:135], v[102:103], v[124:125]
	v_mov_b32_e32 v124, v122
	v_mov_b32_e32 v125, v136
	v_pk_fma_f32 v[120:121], v[124:125], v[104:105], v[120:121]
	v_mov_b32_e32 v136, v123
	v_pk_fma_f32 v[124:125], v[136:137], v[106:107], v[120:121]
	ds_read_b128 v[120:123], v127 offset:38064
	ds_read_b128 v[134:137], v127 offset:38128
	s_waitcnt lgkmcnt(1)
	v_mov_b32_e32 v138, v120
	s_waitcnt lgkmcnt(0)
	v_mov_b32_e32 v139, v134
	v_pk_fma_f32 v[124:125], v[138:139], v[84:85], v[124:125]
	v_mov_b32_e32 v134, v121
	v_pk_fma_f32 v[120:121], v[134:135], v[82:83], v[124:125]
	v_mov_b32_e32 v124, v122
	v_mov_b32_e32 v125, v136
	v_pk_fma_f32 v[120:121], v[124:125], v[80:81], v[120:121]
	v_mov_b32_e32 v136, v123
	v_pk_fma_f32 v[120:121], v[136:137], v[78:79], v[120:121]
	s_nop 0
	v_mul_f32_e64 v122, |v120|, s93
	v_exp_f32_e32 v122, v122
	v_min_f32_e32 v133, 0, v120
	v_min_f32_e32 v134, 0, v121
	v_add_f32_e32 v120, 1.0, v122
	ds_read_b128 v[122:125], v127 offset:38144
	ds_read_b128 v[136:139], v127 offset:38208
	v_log_f32_e32 v120, v120
	s_waitcnt lgkmcnt(1)
	v_mov_b32_e32 v140, v122
	s_waitcnt lgkmcnt(0)
	v_mov_b32_e32 v141, v136
	v_pk_fma_f32 v[140:141], v[140:141], v[76:77], v[108:109]
	v_mov_b32_e32 v136, v123
	v_pk_fma_f32 v[122:123], v[136:137], v[90:91], v[140:141]
	v_mov_b32_e32 v136, v124
	v_mov_b32_e32 v137, v138
	v_pk_fma_f32 v[122:123], v[136:137], v[88:89], v[122:123]
	v_mov_b32_e32 v138, v125
	v_pk_fma_f32 v[140:141], v[138:139], v[86:87], v[122:123]
	ds_read_b128 v[122:125], v127 offset:38160
	ds_read_b128 v[136:139], v127 offset:38224
	v_fmac_f32_e32 v133, 0xbf317218, v120
	v_mul_f32_e64 v120, |v121|, s93
	v_exp_f32_e32 v120, v120
	s_waitcnt lgkmcnt(1)
	v_mov_b32_e32 v142, v122
	s_waitcnt lgkmcnt(0)
	v_mov_b32_e32 v143, v136
	v_pk_fma_f32 v[140:141], v[142:143], v[98:99], v[140:141]
	v_mov_b32_e32 v136, v123
	v_pk_fma_f32 v[122:123], v[136:137], v[94:95], v[140:141]
	v_mov_b32_e32 v136, v124
	v_mov_b32_e32 v137, v138
	v_pk_fma_f32 v[122:123], v[136:137], v[96:97], v[122:123]
	v_mov_b32_e32 v138, v125
	v_pk_fma_f32 v[140:141], v[138:139], v[100:101], v[122:123]
	ds_read_b128 v[122:125], v127 offset:38176
	ds_read_b128 v[136:139], v127 offset:38240
	v_add_f32_e32 v120, 1.0, v120
	v_log_f32_e32 v120, v120
	s_waitcnt lgkmcnt(1)
	v_mov_b32_e32 v142, v122
	s_waitcnt lgkmcnt(0)
	v_mov_b32_e32 v143, v136
	v_pk_fma_f32 v[140:141], v[142:143], v[92:93], v[140:141]
	v_mov_b32_e32 v136, v123
	v_pk_fma_f32 v[122:123], v[136:137], v[102:103], v[140:141]
	v_mov_b32_e32 v136, v124
	v_mov_b32_e32 v137, v138
	v_pk_fma_f32 v[122:123], v[136:137], v[104:105], v[122:123]
	v_mov_b32_e32 v138, v125
	v_pk_fma_f32 v[140:141], v[138:139], v[106:107], v[122:123]
	ds_read_b128 v[122:125], v127 offset:38192
	ds_read_b128 v[136:139], v127 offset:38256
	s_waitcnt lgkmcnt(1)
	v_mov_b32_e32 v142, v122
	s_waitcnt lgkmcnt(0)
	v_mov_b32_e32 v143, v136
	v_pk_fma_f32 v[140:141], v[142:143], v[84:85], v[140:141]
	v_mov_b32_e32 v136, v123
	v_pk_fma_f32 v[122:123], v[136:137], v[82:83], v[140:141]
	v_mov_b32_e32 v136, v124
	v_mov_b32_e32 v137, v138
	v_pk_fma_f32 v[122:123], v[136:137], v[80:81], v[122:123]
	v_mov_b32_e32 v138, v125
	v_pk_fma_f32 v[122:123], v[138:139], v[78:79], v[122:123]
	s_nop 0
	v_mul_f32_e64 v121, |v122|, s93
	v_exp_f32_e32 v121, v121
	v_min_f32_e32 v135, 0, v122
	v_add_f32_e32 v121, 1.0, v121
	v_log_f32_e32 v121, v121
	s_nop 0
	v_fmac_f32_e32 v135, 0xbf317218, v121
	v_mul_f32_e64 v121, |v123|, s93
	v_exp_f32_e32 v122, v121
	v_min_f32_e32 v121, 0, v123
	v_add_f32_e32 v122, 1.0, v122
	v_log_f32_e32 v122, v122
	s_nop 0
	v_fmac_f32_e32 v121, 0xbf317218, v122
	ds_read_b128 v[122:125], v127 offset:38272
	ds_read_b128 v[136:139], v127 offset:38336
	s_waitcnt lgkmcnt(1)
	v_mov_b32_e32 v140, v122
	s_waitcnt lgkmcnt(0)
	v_mov_b32_e32 v141, v136
	v_pk_fma_f32 v[140:141], v[140:141], v[76:77], v[108:109]
	v_mov_b32_e32 v136, v123
	v_pk_fma_f32 v[122:123], v[136:137], v[90:91], v[140:141]
	v_mov_b32_e32 v136, v124
	v_mov_b32_e32 v137, v138
	v_pk_fma_f32 v[122:123], v[136:137], v[88:89], v[122:123]
	v_mov_b32_e32 v138, v125
	v_pk_fma_f32 v[140:141], v[138:139], v[86:87], v[122:123]
	ds_read_b128 v[122:125], v127 offset:38288
	ds_read_b128 v[136:139], v127 offset:38352
	s_waitcnt lgkmcnt(1)
	v_mov_b32_e32 v142, v122
	s_waitcnt lgkmcnt(0)
	v_mov_b32_e32 v143, v136
	v_pk_fma_f32 v[140:141], v[142:143], v[98:99], v[140:141]
	v_mov_b32_e32 v136, v123
	v_pk_fma_f32 v[122:123], v[136:137], v[94:95], v[140:141]
	v_mov_b32_e32 v136, v124
	v_mov_b32_e32 v137, v138
	v_pk_fma_f32 v[122:123], v[136:137], v[96:97], v[122:123]
	v_mov_b32_e32 v138, v125
	v_pk_fma_f32 v[140:141], v[138:139], v[100:101], v[122:123]
	ds_read_b128 v[122:125], v127 offset:38304
	ds_read_b128 v[136:139], v127 offset:38368
	s_waitcnt lgkmcnt(1)
	v_mov_b32_e32 v142, v122
	s_waitcnt lgkmcnt(0)
; #define LAS __attribute__((address_space(3)))
; __device__ __forceinline__ float log_sigmoid_fast(float z) {
;     const float e = __builtin_amdgcn_exp2f(-1.44269504088896f * fabsf(z));
;     return fminf(z, 0.f) - 0.693147180559945f * __builtin_amdgcn_logf(1.0f + e);
; }
; __device__ __forceinline__ void gla_gates(const LAS float* lrs, const float* w2, const float* gbias, int h, int d, int w, float (&pf)[16], float (&sb)[16]) {
;     ...
; #pragma unroll
;     for (int j = 0; j < 16; ++j) {
;         const LAS float* lr = lrs + (w * 16 + j) * 32;
;         f32x2_t z2 = {bf, bb};
; #pragma unroll
;         for (int r4 = 0; r4 < 4; ++r4) { const f32x4 a = *(const LAS f32x4*)(lr + 4 * r4), b = *(const LAS f32x4*)(lr + 16 + 4 * r4);
; #pragma unroll
;             for (int q = 0; q < 4; ++q) { const f32x2_t x2 = {a[q], b[q]}, w2v = {wf[4 * r4 + q], wb[4 * r4 + q]}; z2 = __builtin_elementwise_fma(x2, w2v, z2); } }
;         pf[j] = log_sigmoid_fast(z2[0]) * (1.0f / 16.0f); sb[j] = log_sigmoid_fast(z2[1]) * (1.0f / 16.0f);
	v_mov_b32_e32 v143, v136
	v_pk_fma_f32 v[140:141], v[142:143], v[92:93], v[140:141]
	v_mov_b32_e32 v136, v123
	v_pk_fma_f32 v[122:123], v[136:137], v[102:103], v[140:141]
	v_mov_b32_e32 v136, v124
	v_mov_b32_e32 v137, v138
	v_pk_fma_f32 v[122:123], v[136:137], v[104:105], v[122:123]
	v_mov_b32_e32 v138, v125
	v_pk_fma_f32 v[140:141], v[138:139], v[106:107], v[122:123]
	ds_read_b128 v[122:125], v127 offset:38320
	ds_read_b128 v[136:139], v127 offset:38384
	s_waitcnt lgkmcnt(1)
	v_mov_b32_e32 v142, v122
	s_waitcnt lgkmcnt(0)
	v_mov_b32_e32 v143, v136
	v_pk_fma_f32 v[140:141], v[142:143], v[84:85], v[140:141]
	v_mov_b32_e32 v136, v123
	v_pk_fma_f32 v[122:123], v[136:137], v[82:83], v[140:141]
	v_mov_b32_e32 v136, v124
	v_mov_b32_e32 v137, v138
	v_pk_fma_f32 v[122:123], v[136:137], v[80:81], v[122:123]
	v_mov_b32_e32 v138, v125
	v_pk_fma_f32 v[122:123], v[138:139], v[78:79], v[122:123]
	ds_read_b128 v[138:141], v127 offset:38400
	ds_read_b128 v[142:145], v127 offset:38464
	v_mul_f32_e64 v124, |v122|, s93
	v_exp_f32_e32 v124, v124
	v_min_f32_e32 v136, 0, v122
	v_min_f32_e32 v137, 0, v123
	s_waitcnt lgkmcnt(0)
	v_mov_b32_e32 v125, v142
	v_add_f32_e32 v122, 1.0, v124
	v_mov_b32_e32 v124, v138
	v_pk_fma_f32 v[124:125], v[124:125], v[76:77], v[108:109]
	v_mov_b32_e32 v142, v139
	v_pk_fma_f32 v[124:125], v[142:143], v[90:91], v[124:125]
	v_mov_b32_e32 v138, v140
	v_mov_b32_e32 v139, v144
	v_pk_fma_f32 v[124:125], v[138:139], v[88:89], v[124:125]
	v_mov_b32_e32 v144, v141
	v_pk_fma_f32 v[124:125], v[144:145], v[86:87], v[124:125]
	ds_read_b128 v[138:141], v127 offset:38416
	ds_read_b128 v[142:145], v127 offset:38480
	v_log_f32_e32 v122, v122
	s_waitcnt lgkmcnt(1)
	v_mov_b32_e32 v146, v138
	s_waitcnt lgkmcnt(0)
	v_mov_b32_e32 v147, v142
	v_pk_fma_f32 v[124:125], v[146:147], v[98:99], v[124:125]
	v_mov_b32_e32 v142, v139
	v_pk_fma_f32 v[124:125], v[142:143], v[94:95], v[124:125]
	v_mov_b32_e32 v138, v140
	v_mov_b32_e32 v139, v144
	v_pk_fma_f32 v[124:125], v[138:139], v[96:97], v[124:125]
	v_mov_b32_e32 v144, v141
	v_pk_fma_f32 v[124:125], v[144:145], v[100:101], v[124:125]
	ds_read_b128 v[138:141], v127 offset:38432
	ds_read_b128 v[142:145], v127 offset:38496
	v_fmac_f32_e32 v136, 0xbf317218, v122
	v_mul_f32_e64 v122, |v123|, s93
	v_exp_f32_e32 v122, v122
	s_waitcnt lgkmcnt(1)
	v_mov_b32_e32 v146, v138
	s_waitcnt lgkmcnt(0)
	v_mov_b32_e32 v147, v142
	v_pk_fma_f32 v[124:125], v[146:147], v[92:93], v[124:125]
	v_mov_b32_e32 v142, v139
	v_pk_fma_f32 v[124:125], v[142:143], v[102:103], v[124:125]
	v_mov_b32_e32 v138, v140
	v_mov_b32_e32 v139, v144
	v_pk_fma_f32 v[124:125], v[138:139], v[104:105], v[124:125]
	v_mov_b32_e32 v144, v141
	v_pk_fma_f32 v[124:125], v[144:145], v[106:107], v[124:125]
	ds_read_b128 v[138:141], v127 offset:38448
	ds_read_b128 v[142:145], v127 offset:38512
	v_add_f32_e32 v122, 1.0, v122
	v_log_f32_e32 v122, v122
	s_waitcnt lgkmcnt(1)
	v_mov_b32_e32 v146, v138
	s_waitcnt lgkmcnt(0)
	v_mov_b32_e32 v147, v142
	v_pk_fma_f32 v[124:125], v[146:147], v[84:85], v[124:125]
	v_mov_b32_e32 v142, v139
	v_pk_fma_f32 v[124:125], v[142:143], v[82:83], v[124:125]
	v_mov_b32_e32 v138, v140
	v_mov_b32_e32 v139, v144
	v_pk_fma_f32 v[124:125], v[138:139], v[80:81], v[124:125]
	v_mov_b32_e32 v144, v141
	v_pk_fma_f32 v[124:125], v[144:145], v[78:79], v[124:125]
	ds_read_b128 v[140:143], v127 offset:38528
	ds_read_b128 v[144:147], v127 offset:38592
	v_mul_f32_e64 v123, |v124|, s93
	v_exp_f32_e32 v123, v123
	v_min_f32_e32 v138, 0, v124
	v_add_f32_e32 v123, 1.0, v123
	v_log_f32_e32 v123, v123
	s_nop 0
	v_fmac_f32_e32 v138, 0xbf317218, v123
	v_mul_f32_e64 v123, |v125|, s93
	v_exp_f32_e32 v124, v123
	v_min_f32_e32 v123, 0, v125
	s_waitcnt lgkmcnt(0)
	v_mov_b32_e32 v125, v144
	v_mov_b32_e32 v144, v141
	v_add_f32_e32 v124, 1.0, v124
	v_log_f32_e32 v124, v124
	v_mov_b32_e32 v141, v146
	v_mov_b32_e32 v146, v143
	v_fmac_f32_e32 v123, 0xbf317218, v124
	v_mov_b32_e32 v124, v140
	v_pk_fma_f32 v[124:125], v[124:125], v[76:77], v[108:109]
	v_mov_b32_e32 v140, v142
	v_pk_fma_f32 v[124:125], v[144:145], v[90:91], v[124:125]
	s_nop 0
	v_pk_fma_f32 v[124:125], v[140:141], v[88:89], v[124:125]
	s_nop 0
	v_pk_fma_f32 v[124:125], v[146:147], v[86:87], v[124:125]
	ds_read_b128 v[140:143], v127 offset:38544
	ds_read_b128 v[144:147], v127 offset:38608
	s_waitcnt lgkmcnt(1)
	v_mov_b32_e32 v148, v140
	s_waitcnt lgkmcnt(0)
	v_mov_b32_e32 v149, v144
	v_pk_fma_f32 v[124:125], v[148:149], v[98:99], v[124:125]
	v_mov_b32_e32 v144, v141
	v_pk_fma_f32 v[124:125], v[144:145], v[94:95], v[124:125]
	v_mov_b32_e32 v140, v142
	v_mov_b32_e32 v141, v146
	v_pk_fma_f32 v[124:125], v[140:141], v[96:97], v[124:125]
	v_mov_b32_e32 v146, v143
	v_pk_fma_f32 v[124:125], v[146:147], v[100:101], v[124:125]
	ds_read_b128 v[140:143], v127 offset:38560
	ds_read_b128 v[144:147], v127 offset:38624
	s_waitcnt lgkmcnt(1)
	v_mov_b32_e32 v148, v140
	s_waitcnt lgkmcnt(0)
	v_mov_b32_e32 v149, v144
	v_pk_fma_f32 v[124:125], v[148:149], v[92:93], v[124:125]
	v_mov_b32_e32 v144, v141
	v_pk_fma_f32 v[124:125], v[144:145], v[102:103], v[124:125]
	v_mov_b32_e32 v140, v142
	v_mov_b32_e32 v141, v146
	v_pk_fma_f32 v[124:125], v[140:141], v[104:105], v[124:125]
	v_mov_b32_e32 v146, v143
	v_pk_fma_f32 v[124:125], v[146:147], v[106:107], v[124:125]
	ds_read_b128 v[140:143], v127 offset:38576
	ds_read_b128 v[144:147], v127 offset:38640
	s_waitcnt lgkmcnt(1)
	v_mov_b32_e32 v148, v140
	s_waitcnt lgkmcnt(0)
; #define LAS __attribute__((address_space(3)))
; __device__ __forceinline__ float log_sigmoid_fast(float z) {
;     const float e = __builtin_amdgcn_exp2f(-1.44269504088896f * fabsf(z));
;     return fminf(z, 0.f) - 0.693147180559945f * __builtin_amdgcn_logf(1.0f + e);
; }
; __device__ __forceinline__ void gla_gates(const LAS float* lrs, const float* w2, const float* gbias, int h, int d, int w, float (&pf)[16], float (&sb)[16]) {
;     ...
; #pragma unroll
;     for (int j = 0; j < 16; ++j) {
;         const LAS float* lr = lrs + (w * 16 + j) * 32;
;         f32x2_t z2 = {bf, bb};
; #pragma unroll
;         for (int r4 = 0; r4 < 4; ++r4) { const f32x4 a = *(const LAS f32x4*)(lr + 4 * r4), b = *(const LAS f32x4*)(lr + 16 + 4 * r4);
; #pragma unroll
;             for (int q = 0; q < 4; ++q) { const f32x2_t x2 = {a[q], b[q]}, w2v = {wf[4 * r4 + q], wb[4 * r4 + q]}; z2 = __builtin_elementwise_fma(x2, w2v, z2); } }
;         pf[j] = log_sigmoid_fast(z2[0]) * (1.0f / 16.0f); sb[j] = log_sigmoid_fast(z2[1]) * (1.0f / 16.0f);
	v_mov_b32_e32 v149, v144
	v_pk_fma_f32 v[124:125], v[148:149], v[84:85], v[124:125]
	v_mov_b32_e32 v144, v141
	v_pk_fma_f32 v[124:125], v[144:145], v[82:83], v[124:125]
	v_mov_b32_e32 v140, v142
	v_mov_b32_e32 v141, v146
	v_pk_fma_f32 v[124:125], v[140:141], v[80:81], v[124:125]
	v_mov_b32_e32 v146, v143
	v_pk_fma_f32 v[124:125], v[146:147], v[78:79], v[124:125]
	ds_read_b128 v[142:145], v127 offset:38656
	ds_read_b128 v[146:149], v127 offset:38720
	v_mul_f32_e64 v139, |v124|, s93
	v_exp_f32_e32 v140, v139
	v_min_f32_e32 v139, 0, v124
	s_waitcnt lgkmcnt(1)
	v_mov_b32_e32 v150, v142
	s_waitcnt lgkmcnt(0)
	v_mov_b32_e32 v151, v146
	v_pk_fma_f32 v[150:151], v[150:151], v[76:77], v[108:109]
	v_mov_b32_e32 v146, v143
	v_pk_fma_f32 v[142:143], v[146:147], v[90:91], v[150:151]
	v_mov_b32_e32 v146, v144
	v_mov_b32_e32 v147, v148
	v_pk_fma_f32 v[142:143], v[146:147], v[88:89], v[142:143]
	v_mov_b32_e32 v148, v145
	v_pk_fma_f32 v[150:151], v[148:149], v[86:87], v[142:143]
	ds_read_b128 v[142:145], v127 offset:38672
	ds_read_b128 v[146:149], v127 offset:38736
	v_add_f32_e32 v124, 1.0, v140
	v_log_f32_e32 v124, v124
	v_min_f32_e32 v140, 0, v125
	s_waitcnt lgkmcnt(1)
	v_mov_b32_e32 v152, v142
	s_waitcnt lgkmcnt(0)
	v_mov_b32_e32 v153, v146
	v_pk_fma_f32 v[150:151], v[152:153], v[98:99], v[150:151]
	v_mov_b32_e32 v146, v143
	v_pk_fma_f32 v[142:143], v[146:147], v[94:95], v[150:151]
	v_mov_b32_e32 v146, v144
	v_mov_b32_e32 v147, v148
	v_pk_fma_f32 v[142:143], v[146:147], v[96:97], v[142:143]
	v_mov_b32_e32 v148, v145
	v_pk_fma_f32 v[150:151], v[148:149], v[100:101], v[142:143]
	ds_read_b128 v[142:145], v127 offset:38688
	ds_read_b128 v[146:149], v127 offset:38752
	v_fmac_f32_e32 v139, 0xbf317218, v124
	v_mul_f32_e64 v124, |v125|, s93
	v_exp_f32_e32 v124, v124
	s_waitcnt lgkmcnt(1)
	v_mov_b32_e32 v152, v142
	s_waitcnt lgkmcnt(0)
	v_mov_b32_e32 v153, v146
	v_pk_fma_f32 v[150:151], v[152:153], v[92:93], v[150:151]
	v_mov_b32_e32 v146, v143
	v_pk_fma_f32 v[142:143], v[146:147], v[102:103], v[150:151]
	v_mov_b32_e32 v146, v144
	v_mov_b32_e32 v147, v148
	v_pk_fma_f32 v[142:143], v[146:147], v[104:105], v[142:143]
	v_mov_b32_e32 v148, v145
	v_pk_fma_f32 v[150:151], v[148:149], v[106:107], v[142:143]
	ds_read_b128 v[142:145], v127 offset:38704
	ds_read_b128 v[146:149], v127 offset:38768
	v_add_f32_e32 v124, 1.0, v124
	v_log_f32_e32 v124, v124
	s_waitcnt lgkmcnt(1)
	v_mov_b32_e32 v152, v142
	s_waitcnt lgkmcnt(0)
	v_mov_b32_e32 v153, v146
	v_pk_fma_f32 v[150:151], v[152:153], v[84:85], v[150:151]
	v_mov_b32_e32 v146, v143
	v_pk_fma_f32 v[142:143], v[146:147], v[82:83], v[150:151]
	v_mov_b32_e32 v146, v144
	v_mov_b32_e32 v147, v148
	v_pk_fma_f32 v[142:143], v[146:147], v[80:81], v[142:143]
	v_mov_b32_e32 v148, v145
	v_pk_fma_f32 v[142:143], v[148:149], v[78:79], v[142:143]
	s_nop 0
	v_mul_f32_e64 v125, |v142|, s93
	v_exp_f32_e32 v125, v125
	v_min_f32_e32 v141, 0, v142
	v_add_f32_e32 v125, 1.0, v125
	v_log_f32_e32 v125, v125
	s_nop 0
	v_fmac_f32_e32 v141, 0xbf317218, v125
	v_mul_f32_e64 v125, |v143|, s93
	v_exp_f32_e32 v142, v125
	v_min_f32_e32 v125, 0, v143
	v_add_f32_e32 v142, 1.0, v142
	v_log_f32_e32 v142, v142
	s_nop 0
	v_fmac_f32_e32 v125, 0xbf317218, v142
	ds_read_b128 v[142:145], v127 offset:38784
	ds_read_b128 v[146:149], v127 offset:38848
	s_waitcnt lgkmcnt(1)
	v_mov_b32_e32 v150, v142
	s_waitcnt lgkmcnt(0)
	v_mov_b32_e32 v151, v146
	v_pk_fma_f32 v[76:77], v[150:151], v[76:77], v[108:109]
	v_mov_b32_e32 v146, v143
	v_pk_fma_f32 v[76:77], v[146:147], v[90:91], v[76:77]
	v_mov_b32_e32 v90, v144
	v_mov_b32_e32 v91, v148
	v_pk_fma_f32 v[76:77], v[90:91], v[88:89], v[76:77]
	v_mov_b32_e32 v148, v145
	v_pk_fma_f32 v[76:77], v[148:149], v[86:87], v[76:77]
	ds_read_b128 v[86:89], v127 offset:38800
	ds_read_b128 v[142:145], v127 offset:38864
	s_waitcnt lgkmcnt(1)
	v_mov_b32_e32 v90, v86
	s_waitcnt lgkmcnt(0)
	v_mov_b32_e32 v91, v142
	v_pk_fma_f32 v[76:77], v[90:91], v[98:99], v[76:77]
	v_mov_b32_e32 v142, v87
	v_pk_fma_f32 v[76:77], v[142:143], v[94:95], v[76:77]
	v_mov_b32_e32 v86, v88
	v_mov_b32_e32 v87, v144
	v_pk_fma_f32 v[76:77], v[86:87], v[96:97], v[76:77]
	v_mov_b32_e32 v144, v89
	ds_read_b128 v[86:89], v127 offset:38816
	ds_read_b128 v[94:97], v127 offset:38880
	v_pk_fma_f32 v[76:77], v[144:145], v[100:101], v[76:77]
	s_waitcnt lgkmcnt(1)
	v_mov_b32_e32 v90, v86
	s_waitcnt lgkmcnt(0)
	v_mov_b32_e32 v91, v94
	v_pk_fma_f32 v[76:77], v[90:91], v[92:93], v[76:77]
	v_mov_b32_e32 v94, v87
	v_pk_fma_f32 v[76:77], v[94:95], v[102:103], v[76:77]
	v_mov_b32_e32 v86, v88
	v_mov_b32_e32 v87, v96
	v_pk_fma_f32 v[76:77], v[86:87], v[104:105], v[76:77]
	v_mov_b32_e32 v96, v89
	ds_read_b128 v[86:89], v127 offset:38832
	ds_read_b128 v[90:93], v127 offset:38896
	v_pk_fma_f32 v[76:77], v[96:97], v[106:107], v[76:77]
	s_waitcnt lgkmcnt(1)
	v_mov_b32_e32 v94, v86
	s_waitcnt lgkmcnt(0)
; #define LAS __attribute__((address_space(3)))
; __device__ __forceinline__ int opaque_tid() { int t = threadIdx.x; asm volatile("" : "+v"(t)); return t; }
; __device__ __forceinline__ void gla_gates(const LAS float* lrs, const float* w2, const float* gbias, int h, int d, int w, float (&pf)[16], float (&sb)[16]) {
;     ...
;         pf[j] = log_sigmoid_fast(z2[0]) * (1.0f / 16.0f); sb[j] = log_sigmoid_fast(z2[1]) * (1.0f / 16.0f);
;     }
; #pragma unroll
;     for (int j = 1; j < 16; ++j) pf[j] += pf[j - 1];
; #pragma unroll
;     for (int j = 14; j >= 0; --j) sb[j] += sb[j + 1];
; }
; __device__ __forceinline__ void gla_g1(LAS unsigned char* lds, const bf16_t* KAT, const bf16_t* VAT, const float* LR, const float* w2, const float* gbias, bf16_t* DS, float* DEC, float* BC) {
;     const int tid = opaque_tid(), half = tid >> 8, t256 = tid & 255, d = tid & 63, lane = tid & 63, fr = lane & 15, g = lane >> 4;
;     const int w = __builtin_amdgcn_readfirstlane((tid >> 6) & 3);
;     LAS float* tot = (LAS float*)(lds + half * HALF_LDS);
;     LAS float* ETf = tot + 512; LAS float* ETb = ETf + 64 * ROWP; LAS float* LRS = ETb + 64 * ROWP;
;     for (int it = blockIdx.x; it < CHB * 4 * 32 / 2; it += gridDim.x) {
;         const int uid = it * 2 + half, c = uid & 31, h = (uid >> 5) & 3, bl = uid >> 7;
;         const size_t row0 = (size_t)bl * SEQ + c * 64;
;         const bf16_t* kat = KAT + ((size_t)(bl * 4 + h) * 64) * SEQ + c * 64;
;         const bf16_t* vat = VAT + ((size_t)(bl * 4 + h) * 128) * SEQ + c * 64;
;         const f32x4 l0 = *(const f32x4*)(LR + row0 * 32 + t256 * 8), l1 = *(const f32x4*)(LR + row0 * 32 + t256 * 8 + 4);
;         bf16x8 bfr[2][2], kraw[2][4];
; #pragma unroll
;         for (int t = 0; t < 2; ++t) {
; #pragma unroll
;             for (int e = 0; e < 2; ++e) bfr[t][e] = *(const bf16x8*)(vat + (size_t)(16 * (2 * w + e) + fr) * SEQ + 32 * t + 8 * g);
; #pragma unroll
;             for (int mb = 0; mb < 4; ++mb) kraw[t][mb] = *(const bf16x8*)(kat + (size_t)(16 * mb + fr) * SEQ + 32 * t + 8 * g);
;         }
;         MEMBAR();
;         *(LAS f32x4*)(LRS + t256 * 8) = l0; *(LAS f32x4*)(LRS + t256 * 8 + 4) = l1;
;         __syncthreads();
;         float pf[16], sb[16];
;         gla_gates(LRS, w2, gbias, h, d, w, pf, sb);
;         tot[w * 64 + d] = pf[15]; tot[(4 + w) * 64 + d] = sb[0];
;         __syncthreads();
	v_mov_b32_e32 v95, v90
	v_pk_fma_f32 v[76:77], v[94:95], v[84:85], v[76:77]
	v_mov_b32_e32 v90, v87
	v_pk_fma_f32 v[76:77], v[90:91], v[82:83], v[76:77]
	v_mov_b32_e32 v82, v88
	v_mov_b32_e32 v83, v92
	v_pk_fma_f32 v[76:77], v[82:83], v[80:81], v[76:77]
	v_mov_b32_e32 v92, v89
	v_pk_fma_f32 v[76:77], v[92:93], v[78:79], v[76:77]
	v_add_f32_e32 v89, v110, v111
	v_mul_f32_e64 v78, |v76|, s93
	v_exp_f32_e32 v78, v78
	v_min_f32_e32 v80, 0, v76
	v_min_f32_e32 v109, 0, v77
	v_fmamk_f32 v90, v63, 0x3d800000, v89
	v_add_f32_e32 v76, 1.0, v78
	v_log_f32_e32 v76, v76
	v_pk_mul_f32 v[78:79], v[122:123], s[4:5]
	v_fmamk_f32 v81, v65, 0x3d800000, v90
	v_fmamk_f32 v92, v69, 0x3d800000, v81
	v_fmac_f32_e32 v80, 0xbf317218, v76
	v_mul_f32_e64 v76, |v77|, s93
	v_exp_f32_e32 v76, v76
	v_fmamk_f32 v96, v71, 0x3d800000, v92
	v_fmamk_f32 v100, v75, 0x3d800000, v96
	v_fmamk_f32 v101, v130, 0x3d800000, v100
	v_add_f32_e32 v76, 1.0, v76
	v_log_f32_e32 v76, v76
	v_fmamk_f32 v102, v132, 0x3d800000, v101
	v_fmamk_f32 v108, v133, 0x3d800000, v102
	v_fmamk_f32 v111, v135, 0x3d800000, v108
	v_fmac_f32_e32 v109, 0xbf317218, v76
	v_pk_mul_f32 v[76:77], v[124:125], s[4:5]
	s_nop 0
	v_sub_f32_e32 v63, v140, v76
	v_fmac_f32_e32 v77, 0x3d800000, v109
	v_fmamk_f32 v107, v63, 0x3d800000, v77
	v_sub_f32_e32 v63, v137, v78
	v_add_f32_e32 v106, v107, v79
	v_fmamk_f32 v103, v63, 0x3d800000, v106
	v_pk_mul_f32 v[78:79], v[120:121], s[4:5]
	s_nop 0
	v_sub_f32_e32 v63, v134, v78
	v_add_f32_e32 v99, v103, v79
	v_fmamk_f32 v98, v63, 0x3d800000, v99
	v_pk_mul_f32 v[78:79], v[118:119], s[4:5]
	s_nop 0
	v_sub_f32_e32 v63, v131, v78
	v_add_f32_e32 v97, v98, v79
	v_fmamk_f32 v95, v63, 0x3d800000, v97
	v_pk_mul_f32 v[78:79], v[116:117], s[4:5]
	s_nop 0
	v_sub_f32_e32 v63, v73, v78
	v_add_f32_e32 v94, v95, v79
	v_fmamk_f32 v93, v63, 0x3d800000, v94
	v_pk_mul_f32 v[78:79], v[114:115], s[4:5]
	s_nop 0
	v_sub_f32_e32 v63, v67, v78
	v_add_f32_e32 v76, v93, v79
	v_pk_mul_f32 v[78:79], v[112:113], s[4:5]
	v_fmamk_f32 v112, v136, 0x3d800000, v111
	v_fmamk_f32 v83, v63, 0x3d800000, v76
	v_fmamk_f32 v113, v138, 0x3d800000, v112
	v_sub_f32_e32 v61, v61, v78
	v_add_f32_e32 v73, v83, v79
	v_fmamk_f32 v114, v139, 0x3d800000, v113
	v_fmamk_f32 v67, v61, 0x3d800000, v73
	v_fmamk_f32 v115, v141, 0x3d800000, v114
	v_fmamk_f32 v59, v59, 0x3d800000, v67
	v_add_u32_e32 v61, s2, v49
	v_fmamk_f32 v116, v80, 0x3d800000, v115
	ds_write2st64_b32 v61, v116, v59 offset1:4
	s_waitcnt lgkmcnt(0)
	s_barrier
; #define LAS __attribute__((address_space(3)))
; __device__ __forceinline__ void gla_g1(LAS unsigned char* lds, const bf16_t* KAT, const bf16_t* VAT, const float* LR, const float* w2, const float* gbias, bf16_t* DS, float* DEC, float* BC) {
;     ...
;         float offf = 0.f, offb = 0.f, totf = 0.f, totb = 0.f;
; #pragma unroll
;         for (int q = 0; q < 4; ++q) { const float a = tot[q * 64 + d], b = tot[(4 + q) * 64 + d]; totf += a; totb += b; if (q < w) offf += a; if (q > w) offb += b; }
; #pragma unroll
;         for (int j4 = 0; j4 < 4; ++j4) { f32x4 vf, vb;
; #pragma unroll
;             for (int jj = 0; jj < 4; ++jj) { vf[jj] = __expf(totf - (offf + pf[j4 * 4 + jj])); vb[jj] = __expf(totb - (offb + sb[j4 * 4 + jj])); }
;             *(LAS f32x4*)(ETf + d * ROWP + w * 16 + j4 * 4) = vf; *(LAS f32x4*)(ETb + d * ROWP + w * 16 + j4 * 4) = vb; }
;         if (w == 0) { DEC[((size_t)uid * 2 + 0) * 64 + d] = __expf(totf); DEC[((size_t)uid * 2 + 1) * 64 + d] = __expf(totb); }
	ds_read2st64_b32 v[78:79], v49 offset1:1
	ds_read2st64_b32 v[84:85], v49 offset0:4 offset1:5
	s_waitcnt lgkmcnt(1)
	v_add_f32_e32 v61, 0, v78
	v_cndmask_b32_e64 v65, v61, 0, s[40:41]
	s_waitcnt lgkmcnt(0)
	v_add_f32_e32 v63, 0, v84
	v_add_f32_e32 v69, v65, v79
	v_add_f32_e32 v63, v63, v85
	v_cndmask_b32_e64 v65, v65, v69, s[42:43]
	v_add_f32_e32 v69, 0, v85
	ds_read2st64_b32 v[84:85], v49 offset0:2 offset1:3
	ds_read2st64_b32 v[86:87], v49 offset0:6 offset1:7
	v_add_f32_e32 v61, v61, v79
	v_cndmask_b32_e64 v69, 0, v69, s[40:41]
	s_waitcnt lgkmcnt(1)
	v_add_f32_e32 v80, v61, v84
	v_add_f32_e32 v61, v65, v84
	v_cndmask_b32_e64 v105, v65, v61, s[44:45]
	s_waitcnt lgkmcnt(0)
	v_add_f32_e32 v61, v69, v86
	v_cndmask_b32_e64 v61, 0, v61, s[46:47]
	v_add_f32_e32 v61, v61, v87
	v_mov_b32_e32 v104, v85
	v_cndmask_b32_e64 v79, v61, 0, s[44:45]
	v_add_f32_e32 v61, v110, v105
	v_pk_add_f32 v[80:81], v[80:81], v[104:105]
	v_add_f32_e32 v82, v63, v86
	v_sub_f32_e32 v63, v80, v61
	v_mul_f32_e32 v63, 0x3fb8aa3b, v63
	v_mov_b32_e32 v78, v87
	v_exp_f32_e32 v84, v63
	v_add_f32_e32 v63, v79, v59
	v_pk_add_f32 v[82:83], v[82:83], v[78:79]
	v_add_f32_e32 v65, v89, v105
	v_sub_f32_e32 v59, v82, v63
	v_mul_f32_e32 v59, 0x3fb8aa3b, v59
	v_exp_f32_e32 v88, v59
	v_sub_f32_e32 v59, v80, v65
	v_mul_f32_e32 v59, 0x3fb8aa3b, v59
	v_add_f32_e32 v67, v79, v67
	v_exp_f32_e32 v85, v59
	v_sub_f32_e32 v59, v82, v67
	v_mul_f32_e32 v59, 0x3fb8aa3b, v59
	v_add_f32_e32 v69, v90, v105
	v_exp_f32_e32 v89, v59
	v_sub_f32_e32 v59, v80, v69
	v_mul_f32_e32 v59, 0x3fb8aa3b, v59
	v_add_f32_e32 v71, v79, v73
	v_exp_f32_e32 v86, v59
	v_sub_f32_e32 v59, v82, v71
	v_mul_f32_e32 v59, 0x3fb8aa3b, v59
	v_exp_f32_e32 v90, v59
	v_sub_f32_e32 v59, v80, v81
	v_mul_f32_e32 v59, 0x3fb8aa3b, v59
	v_exp_f32_e32 v87, v59
	v_sub_f32_e32 v59, v82, v83
	v_mul_f32_e32 v59, 0x3fb8aa3b, v59
	v_exp_f32_e32 v91, v59
	v_add_f32_e32 v73, v92, v105
	v_sub_f32_e32 v59, v80, v73
	v_mul_f32_e32 v59, 0x3fb8aa3b, v59
	v_add_f32_e32 v75, v79, v76
	ds_write_b128 v128, v[84:87] offset:2048
	ds_write_b128 v128, v[88:91] offset:19456
	v_exp_f32_e32 v88, v59
	v_sub_f32_e32 v59, v82, v75
	v_mul_f32_e32 v59, 0x3fb8aa3b, v59
	v_add_f32_e32 v76, v96, v105
	v_exp_f32_e32 v92, v59
	v_sub_f32_e32 v59, v80, v76
	v_mul_f32_e32 v59, 0x3fb8aa3b, v59
	v_add_f32_e32 v78, v79, v93
	v_exp_f32_e32 v89, v59
	v_sub_f32_e32 v59, v82, v78
	v_mul_f32_e32 v59, 0x3fb8aa3b, v59
	v_add_f32_e32 v84, v100, v105
	v_exp_f32_e32 v93, v59
	v_sub_f32_e32 v59, v80, v84
	v_mul_f32_e32 v59, 0x3fb8aa3b, v59
	v_add_f32_e32 v85, v79, v94
	v_exp_f32_e32 v90, v59
	v_sub_f32_e32 v59, v82, v85
	v_mul_f32_e32 v59, 0x3fb8aa3b, v59
	v_add_f32_e32 v86, v101, v105
	v_exp_f32_e32 v94, v59
	v_sub_f32_e32 v59, v80, v86
	v_mul_f32_e32 v59, 0x3fb8aa3b, v59
	v_add_f32_e32 v87, v79, v95
	v_exp_f32_e32 v91, v59
	v_sub_f32_e32 v59, v82, v87
	v_mul_f32_e32 v59, 0x3fb8aa3b, v59
	v_exp_f32_e32 v95, v59
	ds_write_b128 v128, v[88:91] offset:2064
	ds_write_b128 v128, v[92:95] offset:19472
	v_add_f32_e32 v88, v102, v105
	v_sub_f32_e32 v59, v80, v88
	v_mul_f32_e32 v59, 0x3fb8aa3b, v59
	v_add_f32_e32 v89, v79, v97
	v_exp_f32_e32 v96, v59
	v_sub_f32_e32 v59, v82, v89
	v_mul_f32_e32 v59, 0x3fb8aa3b, v59
	v_add_f32_e32 v90, v108, v105
	v_exp_f32_e32 v100, v59
	v_sub_f32_e32 v59, v80, v90
	v_mul_f32_e32 v59, 0x3fb8aa3b, v59
	v_add_f32_e32 v91, v79, v98
	v_exp_f32_e32 v97, v59
	v_sub_f32_e32 v59, v82, v91
	v_mul_f32_e32 v59, 0x3fb8aa3b, v59
	v_add_f32_e32 v92, v111, v105
	v_exp_f32_e32 v101, v59
	v_sub_f32_e32 v59, v80, v92
	v_mul_f32_e32 v59, 0x3fb8aa3b, v59
	v_add_f32_e32 v93, v79, v99
	v_exp_f32_e32 v98, v59
	v_sub_f32_e32 v59, v82, v93
	v_mul_f32_e32 v59, 0x3fb8aa3b, v59
	v_add_f32_e32 v94, v112, v105
	v_exp_f32_e32 v102, v59
	v_sub_f32_e32 v59, v80, v94
	v_mul_f32_e32 v59, 0x3fb8aa3b, v59
	v_add_f32_e32 v95, v79, v103
	v_exp_f32_e32 v99, v59
	v_sub_f32_e32 v59, v82, v95
	v_mul_f32_e32 v59, 0x3fb8aa3b, v59
	v_exp_f32_e32 v103, v59
	ds_write_b128 v128, v[96:99] offset:2080
	ds_write_b128 v128, v[100:103] offset:19488
	v_add_f32_e32 v96, v113, v105
	v_sub_f32_e32 v59, v80, v96
	v_mul_f32_e32 v59, 0x3fb8aa3b, v59
	v_add_f32_e32 v97, v79, v106
	v_exp_f32_e32 v102, v59
	v_sub_f32_e32 v59, v82, v97
	v_mul_f32_e32 v59, 0x3fb8aa3b, v59
	v_add_f32_e32 v98, v114, v105
	v_exp_f32_e32 v106, v59
	v_sub_f32_e32 v59, v80, v98
	v_mul_f32_e32 v59, 0x3fb8aa3b, v59
	v_add_f32_e32 v99, v79, v107
	v_exp_f32_e32 v103, v59
	v_sub_f32_e32 v59, v82, v99
	v_mul_f32_e32 v59, 0x3fb8aa3b, v59
	v_add_f32_e32 v100, v105, v115
	v_exp_f32_e32 v107, v59
	v_sub_f32_e32 v59, v80, v100
	v_mul_f32_e32 v59, 0x3fb8aa3b, v59
	v_add_f32_e32 v77, v79, v77
	v_exp_f32_e32 v104, v59
	v_sub_f32_e32 v59, v82, v77
	v_mul_f32_e32 v59, 0x3fb8aa3b, v59
	v_add_f32_e32 v101, v105, v116
	v_exp_f32_e32 v108, v59
	v_sub_f32_e32 v59, v80, v101
	v_mul_f32_e32 v59, 0x3fb8aa3b, v59
	v_fmac_f32_e32 v79, 0x3d800000, v109
	v_exp_f32_e32 v105, v59
	v_sub_f32_e32 v59, v82, v79
	v_mul_f32_e32 v59, 0x3fb8aa3b, v59
	v_exp_f32_e32 v109, v59
	v_ashrrev_i32_e32 v59, 31, v58
	ds_write_b128 v128, v[102:105] offset:2096
	ds_write_b128 v128, v[106:109] offset:19504
	s_cbranch_vccnz .LBB0_499
	s_mov_b64 s[10:11], 0
